# v95 + per-phase s_setprio toggles removed from the K=256 per-layer-embedding GEMM loop as well (32 sites)
# speedup vs baseline: 1.0035x; 1.0035x over previous
.LBB0_1182:
	s_ashr_i32 s15, s14, 31
	s_lshl_b64 s[16:17], s[14:15], 17
	s_add_u32 s16, s30, s16
	v_cmp_lt_i64_e32 vcc, s[4:5], v[230:231]
	s_addc_u32 s17, s31, s17
	s_and_b64 s[60:61], vcc, exec
	s_cselect_b32 s93, s17, s87
	s_cselect_b32 s92, s16, s86
	s_ashr_i32 s13, s12, 31
	s_lshl_b64 s[60:61], s[12:13], 17
	s_add_u32 s84, s23, s60
	s_addc_u32 s85, s28, s61
	s_and_b64 s[60:61], vcc, exec
	s_cselect_b32 s91, s85, s89
	s_cselect_b32 s90, s84, s88
	s_add_i32 s55, 0, 0x10000
	v_add_u32_e32 v212, s55, v8
	ds_read_b128 v[10:13], v212
	ds_read_b128 v[14:17], v212 offset:1024
	ds_read_b128 v[18:21], v212 offset:2048
	ds_read_b128 v[22:25], v212 offset:3072
	s_add_u32 s72, s86, 0x10080
	s_addc_u32 s73, s87, 0
	s_add_i32 s60, s7, 0xc000
	v_lshl_add_u64 v[58:59], s[72:73], 0, v[2:3]
	s_mov_b32 m0, s60
	s_add_i32 s13, s7, 0xe000
	ds_read_b128 v[26:29], v9
	ds_read_b128 v[30:33], v9 offset:1024
	ds_read_b128 v[34:37], v9 offset:2048
	ds_read_b128 v[38:41], v9 offset:3072
	ds_read_b128 v[42:45], v9 offset:4096
	ds_read_b128 v[46:49], v9 offset:5120
	ds_read_b128 v[50:53], v9 offset:6144
	ds_read_b128 v[54:57], v9 offset:7168
	global_load_lds_dwordx4 v[58:59], off
	v_lshl_add_u64 v[58:59], s[72:73], 0, v[4:5]
	s_mov_b32 m0, s13
	s_nop 0
	global_load_lds_dwordx4 v[58:59], off
	s_waitcnt lgkmcnt(8)
	s_barrier
	s_waitcnt lgkmcnt(0)
	s_waitcnt lgkmcnt(0)
	v_mfma_f32_16x16x32_bf16 v[58:61], v[10:13], v[26:29], 0
	v_mfma_f32_16x16x32_bf16 v[62:65], v[18:21], v[26:29], 0
	v_mfma_f32_16x16x32_bf16 v[66:69], v[10:13], v[34:37], 0
	v_mfma_f32_16x16x32_bf16 v[70:73], v[18:21], v[34:37], 0
	v_mfma_f32_16x16x32_bf16 v[74:77], v[10:13], v[42:45], 0
	v_mfma_f32_16x16x32_bf16 v[78:81], v[18:21], v[42:45], 0
	v_mfma_f32_16x16x32_bf16 v[82:85], v[10:13], v[50:53], 0
	v_mfma_f32_16x16x32_bf16 v[86:89], v[18:21], v[50:53], 0
	v_mfma_f32_16x16x32_bf16 v[58:61], v[14:17], v[30:33], v[58:61]
	v_mfma_f32_16x16x32_bf16 v[62:65], v[22:25], v[30:33], v[62:65]
	v_mfma_f32_16x16x32_bf16 v[66:69], v[14:17], v[38:41], v[66:69]
	v_mfma_f32_16x16x32_bf16 v[70:73], v[22:25], v[38:41], v[70:73]
	v_mfma_f32_16x16x32_bf16 v[74:77], v[14:17], v[46:49], v[74:77]
	v_mfma_f32_16x16x32_bf16 v[78:81], v[22:25], v[46:49], v[78:81]
	v_mfma_f32_16x16x32_bf16 v[82:85], v[14:17], v[54:57], v[82:85]
	v_mfma_f32_16x16x32_bf16 v[86:89], v[22:25], v[54:57], v[86:89]
	s_barrier
	s_add_i32 s61, 0, 0x14000
	v_lshl_add_u64 v[186:187], s[88:89], 0, v[0:1]
	s_mov_b64 s[72:73], 0x100
	s_add_i32 s55, s55, s29
	v_add_u32_e32 v213, s61, v8
	v_lshl_add_u64 v[106:107], v[186:187], 0, s[72:73]
	s_mov_b32 m0, s55
	v_lshl_add_u64 v[206:207], s[88:89], 0, v[6:7]
	s_add_i32 s15, s55, 0x2000
	ds_read_b128 v[90:93], v213
	ds_read_b128 v[94:97], v213 offset:1024
	ds_read_b128 v[98:101], v213 offset:2048
	ds_read_b128 v[102:105], v213 offset:3072
	global_load_lds_dwordx4 v[106:107], off
	v_lshl_add_u64 v[106:107], v[206:207], 0, s[72:73]
	s_mov_b32 m0, s15
	s_nop 0
	global_load_lds_dwordx4 v[106:107], off
	s_barrier
	s_waitcnt lgkmcnt(0)
	s_waitcnt lgkmcnt(0)
	v_mfma_f32_16x16x32_bf16 v[106:109], v[90:93], v[26:29], 0
	v_mfma_f32_16x16x32_bf16 v[26:29], v[98:101], v[26:29], 0
	v_mfma_f32_16x16x32_bf16 v[106:109], v[94:97], v[30:33], v[106:109]
	v_mfma_f32_16x16x32_bf16 v[26:29], v[102:105], v[30:33], v[26:29]
	v_mfma_f32_16x16x32_bf16 v[30:33], v[90:93], v[34:37], 0
	v_mfma_f32_16x16x32_bf16 v[34:37], v[98:101], v[34:37], 0
	v_mfma_f32_16x16x32_bf16 v[30:33], v[94:97], v[38:41], v[30:33]
	v_mfma_f32_16x16x32_bf16 v[34:37], v[102:105], v[38:41], v[34:37]
	v_mfma_f32_16x16x32_bf16 v[38:41], v[90:93], v[42:45], 0
	v_mfma_f32_16x16x32_bf16 v[42:45], v[98:101], v[42:45], 0
	v_mfma_f32_16x16x32_bf16 v[38:41], v[94:97], v[46:49], v[38:41]
	v_mfma_f32_16x16x32_bf16 v[42:45], v[102:105], v[46:49], v[42:45]
	v_mfma_f32_16x16x32_bf16 v[46:49], v[90:93], v[50:53], 0
	v_mfma_f32_16x16x32_bf16 v[50:53], v[98:101], v[50:53], 0
	v_mfma_f32_16x16x32_bf16 v[46:49], v[94:97], v[54:57], v[46:49]
	v_mfma_f32_16x16x32_bf16 v[50:53], v[102:105], v[54:57], v[50:53]
	v_lshl_add_u64 v[208:209], s[86:87], 0, v[2:3]
	s_mov_b32 m0, s7
	v_lshl_add_u64 v[138:139], v[208:209], 0, s[72:73]
	v_lshl_add_u64 v[210:211], s[86:87], 0, v[4:5]
	s_barrier
	ds_read_b128 v[54:57], v9 offset:16384
	ds_read_b128 v[110:113], v9 offset:17408
	ds_read_b128 v[114:117], v9 offset:18432
	ds_read_b128 v[118:121], v9 offset:19456
	ds_read_b128 v[122:125], v9 offset:20480
	ds_read_b128 v[126:129], v9 offset:21504
	ds_read_b128 v[130:133], v9 offset:22528
	ds_read_b128 v[134:137], v9 offset:23552
	global_load_lds_dwordx4 v[138:139], off
	v_lshl_add_u64 v[138:139], v[210:211], 0, s[72:73]
	s_mov_b32 m0, s34
	s_nop 0
	global_load_lds_dwordx4 v[138:139], off
	s_barrier
	s_waitcnt lgkmcnt(0)
	s_waitcnt lgkmcnt(0)
	v_mfma_f32_16x16x32_bf16 v[138:141], v[10:13], v[54:57], 0
	v_mfma_f32_16x16x32_bf16 v[146:149], v[10:13], v[114:117], 0
	v_mfma_f32_16x16x32_bf16 v[154:157], v[10:13], v[122:125], 0
	v_mfma_f32_16x16x32_bf16 v[10:13], v[10:13], v[130:133], 0
	v_mfma_f32_16x16x32_bf16 v[138:141], v[14:17], v[110:113], v[138:141]
	v_mfma_f32_16x16x32_bf16 v[142:145], v[18:21], v[54:57], 0
	v_mfma_f32_16x16x32_bf16 v[146:149], v[14:17], v[118:121], v[146:149]
	v_mfma_f32_16x16x32_bf16 v[150:153], v[18:21], v[114:117], 0
	v_mfma_f32_16x16x32_bf16 v[154:157], v[14:17], v[126:129], v[154:157]
	v_mfma_f32_16x16x32_bf16 v[158:161], v[18:21], v[122:125], 0
	v_mfma_f32_16x16x32_bf16 v[10:13], v[14:17], v[134:137], v[10:13]
	v_mfma_f32_16x16x32_bf16 v[14:17], v[18:21], v[130:133], 0
	v_mfma_f32_16x16x32_bf16 v[142:145], v[22:25], v[110:113], v[142:145]
	v_mfma_f32_16x16x32_bf16 v[150:153], v[22:25], v[118:121], v[150:153]
	v_mfma_f32_16x16x32_bf16 v[158:161], v[22:25], v[126:129], v[158:161]
	v_mfma_f32_16x16x32_bf16 v[14:17], v[22:25], v[134:137], v[14:17]
	s_barrier
	s_add_u32 s72, s88, 0x10100
	s_addc_u32 s73, s89, 0
	s_add_i32 s61, s61, s29
	v_lshl_add_u64 v[18:19], s[72:73], 0, v[0:1]
	s_mov_b32 m0, s61
	s_add_i32 s47, s61, 0x2000
	global_load_lds_dwordx4 v[18:19], off
	v_lshl_add_u64 v[18:19], s[72:73], 0, v[6:7]
	s_mov_b32 m0, s47
	s_nop 0
	global_load_lds_dwordx4 v[18:19], off
	s_waitcnt vmcnt(6)
	s_barrier
	v_mfma_f32_16x16x32_bf16 v[18:21], v[90:93], v[54:57], 0
	v_mfma_f32_16x16x32_bf16 v[22:25], v[98:101], v[54:57], 0
	v_mfma_f32_16x16x32_bf16 v[18:21], v[94:97], v[110:113], v[18:21]
	v_mfma_f32_16x16x32_bf16 v[22:25], v[102:105], v[110:113], v[22:25]
	v_mfma_f32_16x16x32_bf16 v[54:57], v[90:93], v[114:117], 0
	v_mfma_f32_16x16x32_bf16 v[110:113], v[98:101], v[114:117], 0
	v_mfma_f32_16x16x32_bf16 v[114:117], v[90:93], v[122:125], 0
	v_mfma_f32_16x16x32_bf16 v[90:93], v[90:93], v[130:133], 0
	v_mfma_f32_16x16x32_bf16 v[54:57], v[94:97], v[118:121], v[54:57]
	v_mfma_f32_16x16x32_bf16 v[110:113], v[102:105], v[118:121], v[110:113]
	v_mfma_f32_16x16x32_bf16 v[114:117], v[94:97], v[126:129], v[114:117]
	v_mfma_f32_16x16x32_bf16 v[118:121], v[98:101], v[122:125], 0
	v_mfma_f32_16x16x32_bf16 v[90:93], v[94:97], v[134:137], v[90:93]
	v_mfma_f32_16x16x32_bf16 v[94:97], v[98:101], v[130:133], 0
	v_mfma_f32_16x16x32_bf16 v[118:121], v[102:105], v[126:129], v[118:121]
	v_mfma_f32_16x16x32_bf16 v[94:97], v[102:105], v[134:137], v[94:97]
	s_add_i32 s74, 0, 0x18000
	v_add_u32_e32 v214, s74, v8
	s_barrier
	ds_read_b128 v[98:101], v214
	ds_read_b128 v[102:105], v214 offset:1024
	ds_read_b128 v[122:125], v214 offset:2048
	ds_read_b128 v[126:129], v214 offset:3072
	s_add_u32 s72, s86, 0x10100
	s_addc_u32 s73, s87, 0
	s_mov_b32 m0, s36
	v_lshl_add_u64 v[190:191], s[72:73], 0, v[2:3]
	ds_read_b128 v[130:133], v9 offset:32768
	ds_read_b128 v[134:137], v9 offset:33792
	ds_read_b128 v[162:165], v9 offset:34816
	ds_read_b128 v[166:169], v9 offset:35840
	ds_read_b128 v[170:173], v9 offset:36864
	ds_read_b128 v[174:177], v9 offset:37888
	ds_read_b128 v[178:181], v9 offset:38912
	ds_read_b128 v[182:185], v9 offset:39936
	global_load_lds_dwordx4 v[190:191], off
	v_lshl_add_u64 v[190:191], s[72:73], 0, v[4:5]
	s_mov_b32 m0, s37
	s_nop 0
	global_load_lds_dwordx4 v[190:191], off
	s_waitcnt lgkmcnt(8)
	s_barrier
	s_waitcnt lgkmcnt(0)
	s_waitcnt lgkmcnt(0)
	v_mfma_f32_16x16x32_bf16 v[58:61], v[98:101], v[130:133], v[58:61]
	v_mfma_f32_16x16x32_bf16 v[62:65], v[122:125], v[130:133], v[62:65]
	v_mfma_f32_16x16x32_bf16 v[66:69], v[98:101], v[162:165], v[66:69]
	v_mfma_f32_16x16x32_bf16 v[70:73], v[122:125], v[162:165], v[70:73]
	v_mfma_f32_16x16x32_bf16 v[74:77], v[98:101], v[170:173], v[74:77]
	v_mfma_f32_16x16x32_bf16 v[78:81], v[122:125], v[170:173], v[78:81]
	v_mfma_f32_16x16x32_bf16 v[82:85], v[98:101], v[178:181], v[82:85]
	v_mfma_f32_16x16x32_bf16 v[86:89], v[122:125], v[178:181], v[86:89]
	v_mfma_f32_16x16x32_bf16 v[58:61], v[102:105], v[134:137], v[58:61]
	v_mfma_f32_16x16x32_bf16 v[62:65], v[126:129], v[134:137], v[62:65]
	v_mfma_f32_16x16x32_bf16 v[66:69], v[102:105], v[166:169], v[66:69]
	v_mfma_f32_16x16x32_bf16 v[70:73], v[126:129], v[166:169], v[70:73]
	v_mfma_f32_16x16x32_bf16 v[74:77], v[102:105], v[174:177], v[74:77]
	v_mfma_f32_16x16x32_bf16 v[78:81], v[126:129], v[174:177], v[78:81]
	v_mfma_f32_16x16x32_bf16 v[82:85], v[102:105], v[182:185], v[82:85]
	v_mfma_f32_16x16x32_bf16 v[86:89], v[126:129], v[182:185], v[86:89]
	s_barrier
	s_add_i32 s75, 0, 0x1c000
	s_add_i32 s74, s74, s29
	v_add_u32_e32 v215, s75, v8
	v_lshl_add_u64 v[186:187], v[186:187], 0, s[76:77]
	s_mov_b32 m0, s74
	s_add_i32 s72, s74, 0x2000
	ds_read_b128 v[190:193], v215
	ds_read_b128 v[194:197], v215 offset:1024
	ds_read_b128 v[198:201], v215 offset:2048
	ds_read_b128 v[202:205], v215 offset:3072
	global_load_lds_dwordx4 v[186:187], off
	v_lshl_add_u64 v[186:187], v[206:207], 0, s[76:77]
	s_mov_b32 m0, s72
	s_nop 0
	global_load_lds_dwordx4 v[186:187], off
	s_barrier
	s_waitcnt lgkmcnt(0)
	s_waitcnt lgkmcnt(0)
	v_mfma_f32_16x16x32_bf16 v[106:109], v[190:193], v[130:133], v[106:109]
	v_mfma_f32_16x16x32_bf16 v[26:29], v[198:201], v[130:133], v[26:29]
	v_mfma_f32_16x16x32_bf16 v[30:33], v[190:193], v[162:165], v[30:33]
	v_mfma_f32_16x16x32_bf16 v[34:37], v[198:201], v[162:165], v[34:37]
	v_mfma_f32_16x16x32_bf16 v[38:41], v[190:193], v[170:173], v[38:41]
	v_mfma_f32_16x16x32_bf16 v[42:45], v[198:201], v[170:173], v[42:45]
	v_mfma_f32_16x16x32_bf16 v[46:49], v[190:193], v[178:181], v[46:49]
	v_mfma_f32_16x16x32_bf16 v[50:53], v[198:201], v[178:181], v[50:53]
	v_mfma_f32_16x16x32_bf16 v[106:109], v[194:197], v[134:137], v[106:109]
	v_mfma_f32_16x16x32_bf16 v[26:29], v[202:205], v[134:137], v[26:29]
	v_mfma_f32_16x16x32_bf16 v[30:33], v[194:197], v[166:169], v[30:33]
	v_mfma_f32_16x16x32_bf16 v[34:37], v[202:205], v[166:169], v[34:37]
	v_mfma_f32_16x16x32_bf16 v[38:41], v[194:197], v[174:177], v[38:41]
	v_mfma_f32_16x16x32_bf16 v[42:45], v[202:205], v[174:177], v[42:45]
	v_mfma_f32_16x16x32_bf16 v[46:49], v[194:197], v[182:185], v[46:49]
	v_mfma_f32_16x16x32_bf16 v[50:53], v[202:205], v[182:185], v[50:53]
	s_mov_b32 m0, s42
	v_lshl_add_u64 v[186:187], v[208:209], 0, s[76:77]
	s_barrier
	ds_read_b128 v[130:133], v9 offset:49152
	ds_read_b128 v[134:137], v9 offset:50176
	ds_read_b128 v[162:165], v9 offset:51200
	ds_read_b128 v[166:169], v9 offset:52224
	ds_read_b128 v[170:173], v9 offset:53248
	ds_read_b128 v[174:177], v9 offset:54272
	ds_read_b128 v[178:181], v9 offset:55296
	ds_read_b128 v[182:185], v9 offset:56320
	global_load_lds_dwordx4 v[186:187], off
	v_lshl_add_u64 v[186:187], v[210:211], 0, s[76:77]
	s_mov_b32 m0, s43
	s_nop 0
	global_load_lds_dwordx4 v[186:187], off
	s_barrier
	s_waitcnt lgkmcnt(0)
	s_waitcnt lgkmcnt(0)
	v_mfma_f32_16x16x32_bf16 v[138:141], v[98:101], v[130:133], v[138:141]
	v_mfma_f32_16x16x32_bf16 v[142:145], v[122:125], v[130:133], v[142:145]
	v_mfma_f32_16x16x32_bf16 v[146:149], v[98:101], v[162:165], v[146:149]
	v_mfma_f32_16x16x32_bf16 v[150:153], v[122:125], v[162:165], v[150:153]
	v_mfma_f32_16x16x32_bf16 v[154:157], v[98:101], v[170:173], v[154:157]
	v_mfma_f32_16x16x32_bf16 v[158:161], v[122:125], v[170:173], v[158:161]
	v_mfma_f32_16x16x32_bf16 v[10:13], v[98:101], v[178:181], v[10:13]
	v_mfma_f32_16x16x32_bf16 v[14:17], v[122:125], v[178:181], v[14:17]
	v_mfma_f32_16x16x32_bf16 v[138:141], v[102:105], v[134:137], v[138:141]
	v_mfma_f32_16x16x32_bf16 v[142:145], v[126:129], v[134:137], v[142:145]
	v_mfma_f32_16x16x32_bf16 v[146:149], v[102:105], v[166:169], v[146:149]
	v_mfma_f32_16x16x32_bf16 v[150:153], v[126:129], v[166:169], v[150:153]
	v_mfma_f32_16x16x32_bf16 v[154:157], v[102:105], v[174:177], v[154:157]
	v_mfma_f32_16x16x32_bf16 v[158:161], v[126:129], v[174:177], v[158:161]
	v_mfma_f32_16x16x32_bf16 v[10:13], v[102:105], v[182:185], v[10:13]
	v_mfma_f32_16x16x32_bf16 v[14:17], v[126:129], v[182:185], v[14:17]
	s_barrier
	s_add_u32 s78, s88, 0x10180
	s_addc_u32 s79, s89, 0
	s_add_i32 s75, s75, s29
	v_lshl_add_u64 v[98:99], s[78:79], 0, v[0:1]
	s_mov_b32 m0, s75
	s_add_i32 s73, s75, 0x2000
	global_load_lds_dwordx4 v[98:99], off
	v_lshl_add_u64 v[98:99], s[78:79], 0, v[6:7]
	s_mov_b32 m0, s73
	s_nop 0
	global_load_lds_dwordx4 v[98:99], off
	s_waitcnt vmcnt(6)
	s_barrier
	v_mfma_f32_16x16x32_bf16 v[18:21], v[190:193], v[130:133], v[18:21]
	v_mfma_f32_16x16x32_bf16 v[22:25], v[198:201], v[130:133], v[22:25]
	v_mfma_f32_16x16x32_bf16 v[54:57], v[190:193], v[162:165], v[54:57]
	v_mfma_f32_16x16x32_bf16 v[98:101], v[198:201], v[162:165], v[110:113]
	v_mfma_f32_16x16x32_bf16 v[102:105], v[190:193], v[170:173], v[114:117]
	v_mfma_f32_16x16x32_bf16 v[110:113], v[198:201], v[170:173], v[118:121]
	v_mfma_f32_16x16x32_bf16 v[90:93], v[190:193], v[178:181], v[90:93]
	v_mfma_f32_16x16x32_bf16 v[94:97], v[198:201], v[178:181], v[94:97]
	v_mfma_f32_16x16x32_bf16 v[18:21], v[194:197], v[134:137], v[18:21]
	v_mfma_f32_16x16x32_bf16 v[22:25], v[202:205], v[134:137], v[22:25]
	v_mfma_f32_16x16x32_bf16 v[54:57], v[194:197], v[166:169], v[54:57]
	v_mfma_f32_16x16x32_bf16 v[98:101], v[202:205], v[166:169], v[98:101]
	v_mfma_f32_16x16x32_bf16 v[102:105], v[194:197], v[174:177], v[102:105]
	v_mfma_f32_16x16x32_bf16 v[110:113], v[202:205], v[174:177], v[110:113]
	v_mfma_f32_16x16x32_bf16 v[90:93], v[194:197], v[182:185], v[90:93]
	v_mfma_f32_16x16x32_bf16 v[94:97], v[202:205], v[182:185], v[94:97]
	s_barrier
	ds_read_b128 v[114:117], v212
	ds_read_b128 v[118:121], v212 offset:1024
	ds_read_b128 v[122:125], v212 offset:2048
	ds_read_b128 v[126:129], v212 offset:3072
	s_add_u32 s78, s86, 0x10180
	s_addc_u32 s79, s87, 0
	s_mov_b32 m0, s60
	v_lshl_add_u64 v[186:187], s[78:79], 0, v[2:3]
	ds_read_b128 v[130:133], v9
	ds_read_b128 v[134:137], v9 offset:1024
	ds_read_b128 v[162:165], v9 offset:2048
	ds_read_b128 v[166:169], v9 offset:3072
	ds_read_b128 v[170:173], v9 offset:4096
	ds_read_b128 v[174:177], v9 offset:5120
	ds_read_b128 v[178:181], v9 offset:6144
	ds_read_b128 v[182:185], v9 offset:7168
	global_load_lds_dwordx4 v[186:187], off
	v_lshl_add_u64 v[186:187], s[78:79], 0, v[4:5]
	s_mov_b32 m0, s13
	s_nop 0
	global_load_lds_dwordx4 v[186:187], off
	s_waitcnt lgkmcnt(8)
	s_barrier
	s_waitcnt lgkmcnt(0)
	s_waitcnt lgkmcnt(0)
	v_mfma_f32_16x16x32_bf16 v[58:61], v[114:117], v[130:133], v[58:61]
	v_mfma_f32_16x16x32_bf16 v[62:65], v[122:125], v[130:133], v[62:65]
	v_mfma_f32_16x16x32_bf16 v[66:69], v[114:117], v[162:165], v[66:69]
	v_mfma_f32_16x16x32_bf16 v[70:73], v[122:125], v[162:165], v[70:73]
	v_mfma_f32_16x16x32_bf16 v[74:77], v[114:117], v[170:173], v[74:77]
	v_mfma_f32_16x16x32_bf16 v[78:81], v[122:125], v[170:173], v[78:81]
	v_mfma_f32_16x16x32_bf16 v[82:85], v[114:117], v[178:181], v[82:85]
	v_mfma_f32_16x16x32_bf16 v[86:89], v[122:125], v[178:181], v[86:89]
	v_mfma_f32_16x16x32_bf16 v[58:61], v[118:121], v[134:137], v[58:61]
	v_mfma_f32_16x16x32_bf16 v[62:65], v[126:129], v[134:137], v[62:65]
	v_mfma_f32_16x16x32_bf16 v[66:69], v[118:121], v[166:169], v[66:69]
	v_mfma_f32_16x16x32_bf16 v[70:73], v[126:129], v[166:169], v[70:73]
	v_mfma_f32_16x16x32_bf16 v[74:77], v[118:121], v[174:177], v[74:77]
	v_mfma_f32_16x16x32_bf16 v[78:81], v[126:129], v[174:177], v[78:81]
	v_mfma_f32_16x16x32_bf16 v[82:85], v[118:121], v[182:185], v[82:85]
	v_mfma_f32_16x16x32_bf16 v[86:89], v[126:129], v[182:185], v[86:89]
	s_barrier
	s_mov_b32 m0, s55
	v_lshl_add_u64 v[186:187], s[90:91], 0, v[0:1]
	ds_read_b128 v[190:193], v213
	ds_read_b128 v[194:197], v213 offset:1024
	ds_read_b128 v[198:201], v213 offset:2048
	ds_read_b128 v[202:205], v213 offset:3072
	global_load_lds_dwordx4 v[186:187], off
	v_lshl_add_u64 v[206:207], s[90:91], 0, v[6:7]
	s_mov_b32 m0, s15
	s_nop 0
	global_load_lds_dwordx4 v[206:207], off
	s_barrier
	s_waitcnt lgkmcnt(0)
	s_waitcnt lgkmcnt(0)
	v_mfma_f32_16x16x32_bf16 v[106:109], v[190:193], v[130:133], v[106:109]
	v_mfma_f32_16x16x32_bf16 v[26:29], v[198:201], v[130:133], v[26:29]
	v_mfma_f32_16x16x32_bf16 v[30:33], v[190:193], v[162:165], v[30:33]
	v_mfma_f32_16x16x32_bf16 v[34:37], v[198:201], v[162:165], v[34:37]
	v_mfma_f32_16x16x32_bf16 v[38:41], v[190:193], v[170:173], v[38:41]
	v_mfma_f32_16x16x32_bf16 v[42:45], v[198:201], v[170:173], v[42:45]
	v_mfma_f32_16x16x32_bf16 v[46:49], v[190:193], v[178:181], v[46:49]
	v_mfma_f32_16x16x32_bf16 v[50:53], v[198:201], v[178:181], v[50:53]
	v_mfma_f32_16x16x32_bf16 v[106:109], v[194:197], v[134:137], v[106:109]
	v_mfma_f32_16x16x32_bf16 v[26:29], v[202:205], v[134:137], v[26:29]
	v_mfma_f32_16x16x32_bf16 v[30:33], v[194:197], v[166:169], v[30:33]
	v_mfma_f32_16x16x32_bf16 v[34:37], v[202:205], v[166:169], v[34:37]
	v_mfma_f32_16x16x32_bf16 v[38:41], v[194:197], v[174:177], v[38:41]
	v_mfma_f32_16x16x32_bf16 v[42:45], v[202:205], v[174:177], v[42:45]
	v_mfma_f32_16x16x32_bf16 v[46:49], v[194:197], v[182:185], v[46:49]
	v_mfma_f32_16x16x32_bf16 v[50:53], v[202:205], v[182:185], v[50:53]
	s_mov_b32 m0, s7
	v_lshl_add_u64 v[208:209], s[92:93], 0, v[2:3]
	s_barrier
	ds_read_b128 v[130:133], v9 offset:16384
	ds_read_b128 v[134:137], v9 offset:17408
	ds_read_b128 v[162:165], v9 offset:18432
	ds_read_b128 v[166:169], v9 offset:19456
	ds_read_b128 v[170:173], v9 offset:20480
	ds_read_b128 v[174:177], v9 offset:21504
	ds_read_b128 v[178:181], v9 offset:22528
	ds_read_b128 v[182:185], v9 offset:23552
	global_load_lds_dwordx4 v[208:209], off
	v_lshl_add_u64 v[210:211], s[92:93], 0, v[4:5]
	s_mov_b32 m0, s34
	s_nop 0
	global_load_lds_dwordx4 v[210:211], off
	s_barrier
	s_waitcnt lgkmcnt(0)
	s_waitcnt lgkmcnt(0)
	v_mfma_f32_16x16x32_bf16 v[138:141], v[114:117], v[130:133], v[138:141]
	v_mfma_f32_16x16x32_bf16 v[142:145], v[122:125], v[130:133], v[142:145]
	v_mfma_f32_16x16x32_bf16 v[146:149], v[114:117], v[162:165], v[146:149]
	v_mfma_f32_16x16x32_bf16 v[150:153], v[122:125], v[162:165], v[150:153]
	v_mfma_f32_16x16x32_bf16 v[154:157], v[114:117], v[170:173], v[154:157]
	v_mfma_f32_16x16x32_bf16 v[158:161], v[122:125], v[170:173], v[158:161]
	v_mfma_f32_16x16x32_bf16 v[10:13], v[114:117], v[178:181], v[10:13]
	v_mfma_f32_16x16x32_bf16 v[14:17], v[122:125], v[178:181], v[14:17]
	v_mfma_f32_16x16x32_bf16 v[138:141], v[118:121], v[134:137], v[138:141]
	v_mfma_f32_16x16x32_bf16 v[142:145], v[126:129], v[134:137], v[142:145]
	v_mfma_f32_16x16x32_bf16 v[146:149], v[118:121], v[166:169], v[146:149]
	v_mfma_f32_16x16x32_bf16 v[150:153], v[126:129], v[166:169], v[150:153]
	v_mfma_f32_16x16x32_bf16 v[154:157], v[118:121], v[174:177], v[154:157]
	v_mfma_f32_16x16x32_bf16 v[158:161], v[126:129], v[174:177], v[158:161]
	v_mfma_f32_16x16x32_bf16 v[10:13], v[118:121], v[182:185], v[10:13]
	v_mfma_f32_16x16x32_bf16 v[14:17], v[126:129], v[182:185], v[14:17]
	s_barrier
	s_add_u32 s60, s90, 0x10000
	s_mov_b32 m0, s61
	s_addc_u32 s61, s91, 0
	v_lshl_add_u64 v[114:115], s[60:61], 0, v[0:1]
	global_load_lds_dwordx4 v[114:115], off
	v_lshl_add_u64 v[114:115], s[60:61], 0, v[6:7]
	s_mov_b32 m0, s47
	s_nop 0
	global_load_lds_dwordx4 v[114:115], off
	s_waitcnt vmcnt(6)
	s_barrier
	v_mfma_f32_16x16x32_bf16 v[18:21], v[190:193], v[130:133], v[18:21]
	v_mfma_f32_16x16x32_bf16 v[22:25], v[198:201], v[130:133], v[22:25]
	v_mfma_f32_16x16x32_bf16 v[54:57], v[190:193], v[162:165], v[54:57]
	v_mfma_f32_16x16x32_bf16 v[98:101], v[198:201], v[162:165], v[98:101]
	v_mfma_f32_16x16x32_bf16 v[102:105], v[190:193], v[170:173], v[102:105]
	v_mfma_f32_16x16x32_bf16 v[110:113], v[198:201], v[170:173], v[110:113]
	v_mfma_f32_16x16x32_bf16 v[90:93], v[190:193], v[178:181], v[90:93]
	v_mfma_f32_16x16x32_bf16 v[94:97], v[198:201], v[178:181], v[94:97]
	v_mfma_f32_16x16x32_bf16 v[18:21], v[194:197], v[134:137], v[18:21]
	v_mfma_f32_16x16x32_bf16 v[22:25], v[202:205], v[134:137], v[22:25]
	v_mfma_f32_16x16x32_bf16 v[54:57], v[194:197], v[166:169], v[54:57]
	v_mfma_f32_16x16x32_bf16 v[98:101], v[202:205], v[166:169], v[98:101]
	v_mfma_f32_16x16x32_bf16 v[102:105], v[194:197], v[174:177], v[102:105]
	v_mfma_f32_16x16x32_bf16 v[110:113], v[202:205], v[174:177], v[110:113]
	v_mfma_f32_16x16x32_bf16 v[90:93], v[194:197], v[182:185], v[90:93]
	v_mfma_f32_16x16x32_bf16 v[94:97], v[202:205], v[182:185], v[94:97]
	s_barrier
	ds_read_b128 v[114:117], v214
	ds_read_b128 v[118:121], v214 offset:1024
	ds_read_b128 v[122:125], v214 offset:2048
	ds_read_b128 v[126:129], v214 offset:3072
	s_add_u32 s60, s92, 0x10000
	s_addc_u32 s61, s93, 0
	s_mov_b32 m0, s36
	v_lshl_add_u64 v[190:191], s[60:61], 0, v[2:3]
	ds_read_b128 v[130:133], v9 offset:32768
	ds_read_b128 v[134:137], v9 offset:33792
	ds_read_b128 v[162:165], v9 offset:34816
	ds_read_b128 v[166:169], v9 offset:35840
	ds_read_b128 v[170:173], v9 offset:36864
	ds_read_b128 v[174:177], v9 offset:37888
	ds_read_b128 v[178:181], v9 offset:38912
	ds_read_b128 v[182:185], v9 offset:39936
	global_load_lds_dwordx4 v[190:191], off
	v_lshl_add_u64 v[190:191], s[60:61], 0, v[4:5]
	s_mov_b32 m0, s37
	s_nop 0
	global_load_lds_dwordx4 v[190:191], off
	s_waitcnt lgkmcnt(8)
	s_barrier
	s_waitcnt lgkmcnt(0)
	s_waitcnt lgkmcnt(0)
	v_mfma_f32_16x16x32_bf16 v[58:61], v[114:117], v[130:133], v[58:61]
	v_mfma_f32_16x16x32_bf16 v[62:65], v[122:125], v[130:133], v[62:65]
	v_mfma_f32_16x16x32_bf16 v[66:69], v[114:117], v[162:165], v[66:69]
	v_mfma_f32_16x16x32_bf16 v[70:73], v[122:125], v[162:165], v[70:73]
	v_mfma_f32_16x16x32_bf16 v[74:77], v[114:117], v[170:173], v[74:77]
	v_mfma_f32_16x16x32_bf16 v[78:81], v[122:125], v[170:173], v[78:81]
	v_mfma_f32_16x16x32_bf16 v[82:85], v[114:117], v[178:181], v[82:85]
	v_mfma_f32_16x16x32_bf16 v[86:89], v[122:125], v[178:181], v[86:89]
	v_mfma_f32_16x16x32_bf16 v[58:61], v[118:121], v[134:137], v[58:61]
	v_mfma_f32_16x16x32_bf16 v[62:65], v[126:129], v[134:137], v[62:65]
	v_mfma_f32_16x16x32_bf16 v[66:69], v[118:121], v[166:169], v[66:69]
	v_mfma_f32_16x16x32_bf16 v[70:73], v[126:129], v[166:169], v[70:73]
	v_mfma_f32_16x16x32_bf16 v[74:77], v[118:121], v[174:177], v[74:77]
	v_mfma_f32_16x16x32_bf16 v[78:81], v[126:129], v[174:177], v[78:81]
	v_mfma_f32_16x16x32_bf16 v[82:85], v[118:121], v[182:185], v[82:85]
	v_mfma_f32_16x16x32_bf16 v[86:89], v[126:129], v[182:185], v[86:89]
	s_barrier
	s_mov_b32 m0, s74
	v_lshl_add_u64 v[186:187], v[186:187], 0, s[40:41]
	ds_read_b128 v[190:193], v215
	ds_read_b128 v[194:197], v215 offset:1024
	ds_read_b128 v[198:201], v215 offset:2048
	ds_read_b128 v[202:205], v215 offset:3072
	global_load_lds_dwordx4 v[186:187], off
	v_lshl_add_u64 v[186:187], v[206:207], 0, s[40:41]
	s_mov_b32 m0, s72
	s_nop 0
	global_load_lds_dwordx4 v[186:187], off
	s_barrier
	s_waitcnt lgkmcnt(0)
	s_waitcnt lgkmcnt(0)
	v_mfma_f32_16x16x32_bf16 v[106:109], v[190:193], v[130:133], v[106:109]
	v_mfma_f32_16x16x32_bf16 v[26:29], v[198:201], v[130:133], v[26:29]
	v_mfma_f32_16x16x32_bf16 v[30:33], v[190:193], v[162:165], v[30:33]
	v_mfma_f32_16x16x32_bf16 v[34:37], v[198:201], v[162:165], v[34:37]
	v_mfma_f32_16x16x32_bf16 v[38:41], v[190:193], v[170:173], v[38:41]
	v_mfma_f32_16x16x32_bf16 v[42:45], v[198:201], v[170:173], v[42:45]
	v_mfma_f32_16x16x32_bf16 v[46:49], v[190:193], v[178:181], v[46:49]
	v_mfma_f32_16x16x32_bf16 v[50:53], v[198:201], v[178:181], v[50:53]
	v_mfma_f32_16x16x32_bf16 v[106:109], v[194:197], v[134:137], v[106:109]
	v_mfma_f32_16x16x32_bf16 v[26:29], v[202:205], v[134:137], v[26:29]
	v_mfma_f32_16x16x32_bf16 v[30:33], v[194:197], v[166:169], v[30:33]
	v_mfma_f32_16x16x32_bf16 v[34:37], v[202:205], v[166:169], v[34:37]
	v_mfma_f32_16x16x32_bf16 v[38:41], v[194:197], v[174:177], v[38:41]
	v_mfma_f32_16x16x32_bf16 v[42:45], v[202:205], v[174:177], v[42:45]
	v_mfma_f32_16x16x32_bf16 v[46:49], v[194:197], v[182:185], v[46:49]
	v_mfma_f32_16x16x32_bf16 v[50:53], v[202:205], v[182:185], v[50:53]
	s_mov_b32 m0, s42
	v_lshl_add_u64 v[186:187], v[208:209], 0, s[40:41]
	s_barrier
	ds_read_b128 v[130:133], v9 offset:49152
	ds_read_b128 v[134:137], v9 offset:50176
	ds_read_b128 v[162:165], v9 offset:51200
	ds_read_b128 v[166:169], v9 offset:52224
	ds_read_b128 v[170:173], v9 offset:53248
	ds_read_b128 v[174:177], v9 offset:54272
	ds_read_b128 v[178:181], v9 offset:55296
	ds_read_b128 v[182:185], v9 offset:56320
	global_load_lds_dwordx4 v[186:187], off
	v_lshl_add_u64 v[186:187], v[210:211], 0, s[40:41]
	s_mov_b32 m0, s43
	s_nop 0
	global_load_lds_dwordx4 v[186:187], off
	s_barrier
	s_waitcnt lgkmcnt(0)
	s_waitcnt lgkmcnt(0)
	v_mfma_f32_16x16x32_bf16 v[138:141], v[114:117], v[130:133], v[138:141]
	v_mfma_f32_16x16x32_bf16 v[142:145], v[122:125], v[130:133], v[142:145]
	v_mfma_f32_16x16x32_bf16 v[146:149], v[114:117], v[162:165], v[146:149]
	v_mfma_f32_16x16x32_bf16 v[150:153], v[122:125], v[162:165], v[150:153]
	v_mfma_f32_16x16x32_bf16 v[154:157], v[114:117], v[170:173], v[154:157]
	v_mfma_f32_16x16x32_bf16 v[158:161], v[122:125], v[170:173], v[158:161]
	v_mfma_f32_16x16x32_bf16 v[10:13], v[114:117], v[178:181], v[10:13]
	v_mfma_f32_16x16x32_bf16 v[14:17], v[122:125], v[178:181], v[14:17]
	v_mfma_f32_16x16x32_bf16 v[138:141], v[118:121], v[134:137], v[138:141]
	v_mfma_f32_16x16x32_bf16 v[142:145], v[126:129], v[134:137], v[142:145]
	v_mfma_f32_16x16x32_bf16 v[146:149], v[118:121], v[166:169], v[146:149]
	v_mfma_f32_16x16x32_bf16 v[150:153], v[126:129], v[166:169], v[150:153]
	v_mfma_f32_16x16x32_bf16 v[154:157], v[118:121], v[174:177], v[154:157]
	v_mfma_f32_16x16x32_bf16 v[158:161], v[126:129], v[174:177], v[158:161]
	v_mfma_f32_16x16x32_bf16 v[10:13], v[118:121], v[182:185], v[10:13]
	v_mfma_f32_16x16x32_bf16 v[14:17], v[126:129], v[182:185], v[14:17]
	s_barrier
	s_add_u32 s60, s90, 0x10080
	s_addc_u32 s61, s91, 0
	s_mov_b32 m0, s75
	v_lshl_add_u64 v[114:115], s[60:61], 0, v[0:1]
	global_load_lds_dwordx4 v[114:115], off
	v_lshl_add_u64 v[114:115], s[60:61], 0, v[6:7]
	s_mov_b32 m0, s73
	s_nop 0
	global_load_lds_dwordx4 v[114:115], off
	s_waitcnt vmcnt(6)
	s_barrier
	v_mfma_f32_16x16x32_bf16 v[18:21], v[190:193], v[130:133], v[18:21]
	v_mfma_f32_16x16x32_bf16 v[22:25], v[198:201], v[130:133], v[22:25]
	v_mfma_f32_16x16x32_bf16 v[54:57], v[190:193], v[162:165], v[54:57]
	v_mfma_f32_16x16x32_bf16 v[98:101], v[198:201], v[162:165], v[98:101]
	v_mfma_f32_16x16x32_bf16 v[102:105], v[190:193], v[170:173], v[102:105]
	v_mfma_f32_16x16x32_bf16 v[110:113], v[198:201], v[170:173], v[110:113]
	v_mfma_f32_16x16x32_bf16 v[90:93], v[190:193], v[178:181], v[90:93]
	v_mfma_f32_16x16x32_bf16 v[94:97], v[198:201], v[178:181], v[94:97]
	v_mfma_f32_16x16x32_bf16 v[18:21], v[194:197], v[134:137], v[18:21]
	v_mfma_f32_16x16x32_bf16 v[22:25], v[202:205], v[134:137], v[22:25]
	v_mfma_f32_16x16x32_bf16 v[54:57], v[194:197], v[166:169], v[54:57]
	v_mfma_f32_16x16x32_bf16 v[98:101], v[202:205], v[166:169], v[98:101]
	v_mfma_f32_16x16x32_bf16 v[102:105], v[194:197], v[174:177], v[102:105]
	v_mfma_f32_16x16x32_bf16 v[110:113], v[202:205], v[174:177], v[110:113]
	v_mfma_f32_16x16x32_bf16 v[90:93], v[194:197], v[182:185], v[90:93]
	v_mfma_f32_16x16x32_bf16 v[94:97], v[202:205], v[182:185], v[94:97]
	v_mov_b32_e32 v115, v252
	s_lshl_b32 s6, s6, 8
	s_barrier
	s_add_i32 s6, s6, s38
	v_and_or_b32 v114, v115, 15, s6
	s_lshl_b32 s6, s45, 8
	v_lshrrev_b32_e32 v115, 1, v115
	v_and_or_b32 v115, v115, 24, s6
	v_or_b32_e32 v116, s39, v115
	v_ashrrev_i32_e32 v115, 31, v114
	v_ashrrev_i32_e32 v117, 31, v116
	v_lshlrev_b64 v[118:119], 11, v[114:115]
	v_lshl_add_u64 v[118:119], s[24:25], 0, v[118:119]
	v_lshlrev_b64 v[116:117], 1, v[116:117]
	v_lshl_add_u64 v[118:119], v[118:119], 0, v[116:117]
	v_cvt_pk_bf16_f32 v58, v58, v59
	v_cvt_pk_bf16_f32 v59, v60, v61
	v_cvt_pk_bf16_f32 v60, v62, v63
	v_cvt_pk_bf16_f32 v61, v64, v65
	global_store_dwordx4 v[118:119], v[58:61], off
	s_mov_b32 s6, 0x40000
	s_mov_b64 s[60:61], 0x40000
	v_cvt_pk_bf16_f32 v60, v26, v27
	v_or_b32_e32 v26, 16, v114
	v_ashrrev_i32_e32 v27, 31, v26
	v_lshlrev_b64 v[26:27], 11, v[26:27]
	v_cvt_pk_bf16_f32 v58, v106, v107
	v_cvt_pk_bf16_f32 v59, v108, v109
	v_cvt_pk_bf16_f32 v61, v28, v29
	v_lshl_add_u64 v[26:27], s[24:25], 0, v[26:27]
	global_store_dwordx4 v[118:119], v[58:61], off offset:256
	v_cvt_pk_bf16_f32 v28, v70, v71
	v_cvt_pk_bf16_f32 v29, v72, v73
	v_lshl_add_u64 v[58:59], v[26:27], 0, v[116:117]
	v_cvt_pk_bf16_f32 v26, v66, v67
	v_cvt_pk_bf16_f32 v27, v68, v69
	global_store_dwordx4 v[58:59], v[26:29], off
	v_cvt_pk_bf16_f32 v18, v18, v19
	v_cvt_pk_bf16_f32 v19, v20, v21
	v_cvt_pk_bf16_f32 v26, v30, v31
	v_cvt_pk_bf16_f32 v27, v32, v33
	v_cvt_pk_bf16_f32 v28, v34, v35
	v_cvt_pk_bf16_f32 v29, v36, v37
	global_store_dwordx4 v[58:59], v[26:29], off offset:256
	v_add_co_u32_e32 v32, vcc, s6, v118
	s_nop 0
	v_or_b32_e32 v26, 32, v114
	v_ashrrev_i32_e32 v27, 31, v26
	v_lshlrev_b64 v[26:27], 11, v[26:27]
	v_lshl_add_u64 v[26:27], s[24:25], 0, v[26:27]
	v_lshl_add_u64 v[30:31], v[26:27], 0, v[116:117]
	v_cvt_pk_bf16_f32 v26, v74, v75
	v_cvt_pk_bf16_f32 v27, v76, v77
	v_cvt_pk_bf16_f32 v28, v78, v79
	v_cvt_pk_bf16_f32 v29, v80, v81
	global_store_dwordx4 v[30:31], v[26:29], off
	v_addc_co_u32_e32 v33, vcc, 0, v119, vcc
	s_nop 0
	v_cvt_pk_bf16_f32 v26, v38, v39
	v_cvt_pk_bf16_f32 v27, v40, v41
	v_cvt_pk_bf16_f32 v28, v42, v43
	v_cvt_pk_bf16_f32 v29, v44, v45
	global_store_dwordx4 v[30:31], v[26:29], off offset:256
	s_mov_b32 s6, 0x48000
	v_cvt_pk_bf16_f32 v20, v22, v23
	v_or_b32_e32 v26, 48, v114
	v_ashrrev_i32_e32 v27, 31, v26
	v_lshlrev_b64 v[26:27], 11, v[26:27]
	v_lshl_add_u64 v[26:27], s[24:25], 0, v[26:27]
	v_lshl_add_u64 v[30:31], v[26:27], 0, v[116:117]
	v_cvt_pk_bf16_f32 v26, v82, v83
	v_cvt_pk_bf16_f32 v27, v84, v85
	v_cvt_pk_bf16_f32 v28, v86, v87
	v_cvt_pk_bf16_f32 v29, v88, v89
	global_store_dwordx4 v[30:31], v[26:29], off
	v_cvt_pk_bf16_f32 v21, v24, v25
	v_add_co_u32_e32 v24, vcc, s6, v118
	v_cvt_pk_bf16_f32 v26, v46, v47
	v_cvt_pk_bf16_f32 v27, v48, v49
	v_cvt_pk_bf16_f32 v28, v50, v51
	v_cvt_pk_bf16_f32 v29, v52, v53
	global_store_dwordx4 v[30:31], v[26:29], off offset:256
	v_lshl_add_u64 v[30:31], v[118:119], 0, s[60:61]
	global_store_dwordx4 v[30:31], v[18:21], off offset:256
	v_addc_co_u32_e32 v25, vcc, 0, v119, vcc
	s_nop 0
	v_cvt_pk_bf16_f32 v18, v146, v147
	v_cvt_pk_bf16_f32 v19, v148, v149
	v_cvt_pk_bf16_f32 v20, v150, v151
	v_cvt_pk_bf16_f32 v21, v152, v153
	s_mov_b32 s6, 0x50000
	s_mov_b64 s[60:61], 0x48000
	global_store_dwordx4 v[24:25], v[18:21], off
	v_add_co_u32_e32 v24, vcc, s6, v118
	v_lshl_add_u64 v[22:23], v[118:119], 0, s[60:61]
	v_cvt_pk_bf16_f32 v18, v54, v55
	v_cvt_pk_bf16_f32 v19, v56, v57
	v_cvt_pk_bf16_f32 v20, v98, v99
	v_cvt_pk_bf16_f32 v21, v100, v101
	v_addc_co_u32_e32 v25, vcc, 0, v119, vcc
	s_mov_b32 s6, 0x58000
	global_store_dwordx4 v[22:23], v[18:21], off offset:256
	s_mov_b64 s[60:61], 0x50000
	v_cvt_pk_bf16_f32 v10, v10, v11
	v_cvt_pk_bf16_f32 v18, v154, v155
	v_cvt_pk_bf16_f32 v19, v156, v157
	v_cvt_pk_bf16_f32 v20, v158, v159
	v_cvt_pk_bf16_f32 v21, v160, v161
	v_cvt_pk_bf16_f32 v11, v12, v13
	v_cvt_pk_bf16_f32 v12, v14, v15
	v_add_co_u32_e32 v14, vcc, s6, v118
	v_lshl_add_u64 v[22:23], v[118:119], 0, s[60:61]
	global_store_dwordx4 v[24:25], v[18:21], off
	s_mov_b64 s[60:61], 0x58000
	v_cvt_pk_bf16_f32 v13, v16, v17
	v_cvt_pk_bf16_f32 v18, v102, v103
	v_cvt_pk_bf16_f32 v19, v104, v105
	v_cvt_pk_bf16_f32 v20, v110, v111
	v_cvt_pk_bf16_f32 v21, v112, v113
	v_addc_co_u32_e32 v15, vcc, 0, v119, vcc
	v_cvt_pk_bf16_f32 v26, v138, v139
	v_cvt_pk_bf16_f32 v27, v140, v141
	v_cvt_pk_bf16_f32 v28, v142, v143
	v_cvt_pk_bf16_f32 v29, v144, v145
	global_store_dwordx4 v[22:23], v[18:21], off offset:256
	global_store_dwordx4 v[14:15], v[10:13], off
	s_add_i32 s44, s44, s20
	v_lshl_add_u64 v[18:19], v[118:119], 0, s[60:61]
	v_cvt_pk_bf16_f32 v10, v90, v91
	v_cvt_pk_bf16_f32 v11, v92, v93
	v_cvt_pk_bf16_f32 v12, v94, v95
	v_cvt_pk_bf16_f32 v13, v96, v97
	s_andn2_b64 vcc, exec, s[2:3]
	s_mov_b32 s45, s12
	s_mov_b32 s6, s14
	s_mov_b64 s[88:89], s[84:85]
	s_mov_b64 s[86:87], s[16:17]
	global_store_dwordx4 v[32:33], v[26:29], off
	global_store_dwordx4 v[18:19], v[10:13], off offset:256
	s_cbranch_vccz .LBB0_1188
